# GLA step 2a software-pipelined: bpermute triple of d-tile k overlapped with d-tile k+1 math; masked writes one stage later, no branches
# speedup vs baseline: 1.0369x; 1.0058x over previous
.LBB0_334:
	s_waitcnt vmcnt(6)
	v_perm_b32 v2, v70, v66, s33
	v_perm_b32 v66, v70, v66, s72
	ds_write2_b32 v168, v2, v66 offset1:32
	v_perm_b32 v2, v71, v67, s33
	ds_write_b32 v169, v2 offset:24576
	v_perm_b32 v2, v71, v67, s72
	ds_write_b32 v170, v2 offset:24576
	v_perm_b32 v2, v72, v68, s33
	ds_write_b32 v171, v2 offset:24576
	v_perm_b32 v2, v72, v68, s72
	ds_write_b32 v172, v2 offset:24576
	v_perm_b32 v2, v73, v69, s33
	ds_write_b32 v173, v2 offset:24576
	v_perm_b32 v2, v73, v69, s72
	ds_write_b32 v174, v2 offset:24576
	s_waitcnt vmcnt(5)
	v_perm_b32 v2, v62, v58, s33
	v_perm_b32 v58, v62, v58, s72
	ds_write2_b32 v175, v2, v58 offset1:32
	v_perm_b32 v2, v63, v59, s33
	ds_write_b32 v176, v2 offset:24576
	v_perm_b32 v2, v63, v59, s72
	ds_write_b32 v177, v2 offset:24576
	v_perm_b32 v2, v64, v60, s33
	ds_write_b32 v178, v2 offset:24576
	v_perm_b32 v2, v64, v60, s72
	ds_write_b32 v179, v2 offset:24576
	v_perm_b32 v2, v65, v61, s33
	ds_write_b32 v180, v2 offset:24576
	v_perm_b32 v2, v65, v61, s72
	s_and_b64 vcc, exec, s[4:5]
	v_mov_b64_e32 v[90:91], v[108:109]
	v_mov_b64_e32 v[96:97], v[108:109]
	v_mov_b64_e32 v[94:95], v[116:117]
	v_mov_b64_e32 v[92:93], v[118:119]
	v_mov_b32_e32 v211, v117
	v_mov_b32_e32 v215, v117
	v_mov_b32_e32 v219, v117
	v_mov_b32_e32 v210, v116
	v_mov_b32_e32 v135, v119
	v_mov_b32_e32 v209, v118
	v_mov_b32_e32 v214, v116
	v_mov_b32_e32 v212, v119
	v_mov_b32_e32 v213, v118
	v_mov_b32_e32 v218, v116
	v_mov_b32_e32 v216, v119
	v_mov_b32_e32 v217, v118
	ds_write_b32 v181, v2 offset:24576
	s_cbranch_vccnz .LBB0_303
	s_waitcnt vmcnt(4)
	v_cndmask_b32_e64 v57, 0, v57, s[10:11]
	v_cndmask_b32_e64 v56, 0, v56, s[10:11]
	v_cndmask_b32_e64 v55, 0, v55, s[10:11]
	v_cndmask_b32_e64 v54, 0, v54, s[10:11]
	s_nop 1
	v_mfma_f32_16x16x32_bf16 v[58:61], v[54:57], v[6:9], 0
	v_mfma_f32_16x16x32_bf16 v[62:65], v[54:57], v[10:13], 0
	s_nop 6
	v_add_f32_e32 v2, v111, v58
	v_min_f32_e32 v67, 0, v2
	v_mul_f32_e64 v2, |v2|, s73
	v_exp_f32_e32 v2, v2
	s_nop 0
	v_add_f32_e32 v2, 1.0, v2
	v_log_f32_e32 v2, v2
	s_nop 0
	v_mul_f32_e32 v58, 0x3f317217, v2
	v_fma_f32 v58, v2, s67, -v58
	v_fmac_f32_e32 v58, 0x3377d1cf, v2
	v_fmac_f32_e32 v58, 0x3f317217, v2
	v_mov_b32_e32 v2, v58
	v_mov_b32_e32 v58, 0
	v_sub_f32_e32 v69, v2, v58
	v_add_f32_e32 v2, v111, v59
	v_min_f32_e32 v58, 0, v2
	v_mul_f32_e64 v2, |v2|, s73
	v_exp_f32_e32 v2, v2
	s_nop 0
	v_add_f32_e32 v2, 1.0, v2
	v_log_f32_e32 v2, v2
	s_nop 0
	v_mul_f32_e32 v59, 0x3f317217, v2
	v_fma_f32 v59, v2, s67, -v59
	v_fmac_f32_e32 v59, 0x3377d1cf, v2
	v_fmac_f32_e32 v59, 0x3f317217, v2
	v_mov_b32_e32 v2, v59
	v_mov_b32_e32 v59, 0
	v_sub_f32_e32 v2, v2, v59
	v_sub_f32_e32 v70, v58, v2
	v_add_f32_e32 v2, v111, v60
	v_min_f32_e32 v58, 0, v2
	v_mul_f32_e64 v2, |v2|, s73
	v_exp_f32_e32 v2, v2
	s_nop 0
	v_add_f32_e32 v2, 1.0, v2
	v_log_f32_e32 v2, v2
	s_nop 0
	v_mul_f32_e32 v59, 0x3f317217, v2
	v_fma_f32 v59, v2, s67, -v59
	v_fmac_f32_e32 v59, 0x3377d1cf, v2
	v_fmac_f32_e32 v59, 0x3f317217, v2
	v_mov_b32_e32 v2, v59
	v_mov_b32_e32 v59, 0
	v_sub_f32_e32 v2, v2, v59
	v_sub_f32_e32 v71, v58, v2
	v_add_f32_e32 v2, v111, v61
	v_min_f32_e32 v58, 0, v2
	v_mul_f32_e64 v2, |v2|, s73
	v_exp_f32_e32 v2, v2
	s_nop 0
	v_add_f32_e32 v2, 1.0, v2
	v_log_f32_e32 v2, v2
	s_nop 0
	v_mul_f32_e32 v59, 0x3f317217, v2
	v_fma_f32 v59, v2, s67, -v59
	v_fmac_f32_e32 v59, 0x3377d1cf, v2
	v_fmac_f32_e32 v59, 0x3f317217, v2
	v_mov_b32_e32 v2, v59
	v_mov_b32_e32 v59, 0
	v_sub_f32_e32 v2, v2, v59
	v_sub_f32_e32 v72, v58, v2
	v_add_f32_e32 v2, v139, v62
	v_min_f32_e32 v66, 0, v2
	v_mul_f32_e64 v2, |v2|, s73
	v_exp_f32_e32 v2, v2
	v_and_b32_e32 v62, 64, v1
	v_add_f32_e32 v2, 1.0, v2
	v_log_f32_e32 v2, v2
	s_nop 0
	v_mul_f32_e32 v58, 0x3f317217, v2
	v_fma_f32 v58, v2, s67, -v58
	v_fmac_f32_e32 v58, 0x3377d1cf, v2
	v_fmac_f32_e32 v58, 0x3f317217, v2
	v_mov_b32_e32 v2, v58
	v_mov_b32_e32 v58, 0
	v_sub_f32_e32 v68, v2, v58
	v_add_u32_e32 v2, -16, v1
	v_pk_add_f32 v[58:59], v[66:67], v[68:69] neg_lo:[0,1] neg_hi:[0,1]
	v_cmp_lt_i32_e32 vcc, v2, v62
	v_subrev_u32_e32 v66, 32, v1
	v_pk_mul_f32 v[90:91], v[58:59], s[96:97] op_sel_hi:[1,0]
	v_cndmask_b32_e32 v2, v2, v1, vcc
	v_cmp_lt_i32_e32 vcc, v66, v62
	v_fmamk_f32 v94, v70, 0x3d800000, v91
	v_fmamk_f32 v93, v71, 0x3d800000, v94
	v_cndmask_b32_e32 v66, v66, v1, vcc
	v_lshlrev_b32_e32 v67, 2, v66
	v_subrev_u32_e32 v66, 48, v1
	v_cmp_lt_i32_e32 vcc, v66, v62
	v_lshlrev_b32_e32 v2, 2, v2
	v_or_b32_e32 v62, v62, v166
	v_cndmask_b32_e32 v66, v66, v1, vcc
	v_fmamk_f32 v92, v72, 0x3d800000, v93
	v_lshlrev_b32_e32 v68, 2, v66
	v_lshlrev_b32_e32 v66, 2, v62
	ds_bpermute_b32 v223, v2, v92
	ds_bpermute_b32 v224, v67, v92
	ds_bpermute_b32 v225, v68, v92
	v_mfma_f32_16x16x32_bf16 v[58:61], v[54:57], v[14:17], 0
	v_mfma_f32_16x16x32_bf16 v[54:57], v[54:57], v[18:21], 0
	v_add_f32_e32 v62, v139, v63
	v_min_f32_e32 v63, 0, v62
	v_mul_f32_e64 v62, |v62|, s73
	v_exp_f32_e32 v62, v62
	s_nop 0
	v_add_f32_e32 v62, 1.0, v62
	v_log_f32_e32 v62, v62
	s_nop 0
	v_mul_f32_e32 v69, 0x3f317217, v62
	v_fma_f32 v69, v62, s67, -v69
	v_fmac_f32_e32 v69, 0x3377d1cf, v62
	v_fmac_f32_e32 v69, 0x3f317217, v62
	v_mov_b32_e32 v62, v69
	v_mov_b32_e32 v69, 0
	v_sub_f32_e32 v62, v62, v69
	v_sub_f32_e32 v62, v63, v62
	v_add_f32_e32 v63, v139, v64
	v_min_f32_e32 v64, 0, v63
	v_mul_f32_e64 v63, |v63|, s73
	v_exp_f32_e32 v63, v63
	v_fmamk_f32 v210, v62, 0x3d800000, v90
	v_add_f32_e32 v63, 1.0, v63
	v_log_f32_e32 v63, v63
	s_nop 0
	v_mul_f32_e32 v69, 0x3f317217, v63
	v_fma_f32 v69, v63, s67, -v69
	v_fmac_f32_e32 v69, 0x3377d1cf, v63
	v_fmac_f32_e32 v69, 0x3f317217, v63
	v_mov_b32_e32 v63, v69
	v_mov_b32_e32 v69, 0
	v_sub_f32_e32 v63, v63, v69
	v_sub_f32_e32 v63, v64, v63
	v_add_f32_e32 v64, v139, v65
	v_min_f32_e32 v65, 0, v64
	v_mul_f32_e64 v64, |v64|, s73
	v_exp_f32_e32 v64, v64
	v_fmamk_f32 v135, v63, 0x3d800000, v210
	v_add_f32_e32 v64, 1.0, v64
	v_log_f32_e32 v64, v64
	s_nop 0
	v_mul_f32_e32 v69, 0x3f317217, v64
	v_fma_f32 v69, v64, s67, -v69
	v_fmac_f32_e32 v69, 0x3377d1cf, v64
	v_fmac_f32_e32 v69, 0x3f317217, v64
	v_mov_b32_e32 v64, v69
	v_mov_b32_e32 v69, 0
	v_sub_f32_e32 v64, v64, v69
	v_sub_f32_e32 v64, v65, v64
	v_fmamk_f32 v209, v64, 0x3d800000, v135
	s_waitcnt lgkmcnt(0)
	v_cndmask_b32_e64 v223, v223, 0, s[6:7]
	v_cndmask_b32_e64 v224, 0, v224, s[12:13]
	v_add_f32_e32 v223, v223, v224
	v_cndmask_b32_e64 v224, 0, v225, s[8:9]
	v_add_f32_e32 v95, v223, v224
	v_add_f32_e32 v223, v95, v92
	ds_bpermute_b32 v220, v66, v223
	ds_bpermute_b32 v226, v2, v209
	ds_bpermute_b32 v227, v67, v209
	ds_bpermute_b32 v228, v68, v209
	v_add_f32_e32 v58, v140, v58
	v_min_f32_e32 v63, 0, v58
	v_mul_f32_e64 v58, |v58|, s73
	v_exp_f32_e32 v58, v58
	v_add_f32_e32 v54, v141, v54
	v_add_f32_e32 v58, 1.0, v58
	s_nop 0
	v_log_f32_e32 v58, v58
	s_nop 0
	v_mul_f32_e32 v62, 0x3f317217, v58
	v_fma_f32 v62, v58, s67, -v62
	v_fmac_f32_e32 v62, 0x3377d1cf, v58
	v_fmac_f32_e32 v62, 0x3f317217, v58
	v_mov_b32_e32 v58, v62
	v_mov_b32_e32 v62, 0
	v_sub_f32_e32 v65, v58, v62
	v_add_f32_e32 v58, v140, v59
	v_min_f32_e32 v59, 0, v58
	v_mul_f32_e64 v58, |v58|, s73
	v_exp_f32_e32 v58, v58
	s_nop 0
	v_add_f32_e32 v58, 1.0, v58
	v_log_f32_e32 v58, v58
	s_nop 0
	v_mul_f32_e32 v62, 0x3f317217, v58
	v_fma_f32 v62, v58, s67, -v62
	v_fmac_f32_e32 v62, 0x3377d1cf, v58
	v_fmac_f32_e32 v62, 0x3f317217, v58
	v_mov_b32_e32 v58, v62
	v_mov_b32_e32 v62, 0
	v_sub_f32_e32 v58, v58, v62
	v_sub_f32_e32 v69, v59, v58
	v_add_f32_e32 v58, v140, v60
	v_min_f32_e32 v59, 0, v58
	v_mul_f32_e64 v58, |v58|, s73
	v_exp_f32_e32 v58, v58
	v_min_f32_e32 v62, 0, v54
	v_mul_f32_e64 v54, |v54|, s73
	v_exp_f32_e32 v54, v54
	v_add_f32_e32 v58, 1.0, v58
	v_add_f32_e32 v54, 1.0, v54
	s_nop 0
	v_log_f32_e32 v58, v58
	s_nop 0
	v_mul_f32_e32 v60, 0x3f317217, v58
	v_fma_f32 v60, v58, s67, -v60
	v_fmac_f32_e32 v60, 0x3377d1cf, v58
	v_fmac_f32_e32 v60, 0x3f317217, v58
	v_mov_b32_e32 v58, v60
	v_mov_b32_e32 v60, 0
	v_sub_f32_e32 v58, v58, v60
	v_sub_f32_e32 v60, v59, v58
	v_add_f32_e32 v58, v140, v61
	v_min_f32_e32 v59, 0, v58
	v_mul_f32_e64 v58, |v58|, s73
	v_exp_f32_e32 v58, v58
	s_nop 0
	v_add_f32_e32 v58, 1.0, v58
	v_log_f32_e32 v58, v58
	s_nop 0
	v_mul_f32_e32 v61, 0x3f317217, v58
	v_fma_f32 v61, v58, s67, -v61
	v_fmac_f32_e32 v61, 0x3377d1cf, v58
	v_fmac_f32_e32 v61, 0x3f317217, v58
	v_mov_b32_e32 v58, v61
	v_mov_b32_e32 v61, 0
	v_sub_f32_e32 v58, v58, v61
	v_sub_f32_e32 v61, v59, v58
	s_nop 0
	v_log_f32_e32 v54, v54
	s_nop 0
	v_mul_f32_e32 v58, 0x3f317217, v54
	v_fma_f32 v58, v54, s67, -v58
	v_fmac_f32_e32 v58, 0x3377d1cf, v54
	v_fmac_f32_e32 v58, 0x3f317217, v54
	v_mov_b32_e32 v54, v58
	v_mov_b32_e32 v58, 0
	v_sub_f32_e32 v64, v54, v58
	v_pk_add_f32 v[58:59], v[62:63], v[64:65] neg_lo:[0,1] neg_hi:[0,1]
	s_nop 0
	v_pk_mul_f32 v[96:97], v[58:59], s[96:97] op_sel_hi:[1,0]
	s_nop 0
	v_fmamk_f32 v214, v69, 0x3d800000, v97
	v_fmamk_f32 v212, v60, 0x3d800000, v214
	v_fmamk_f32 v213, v61, 0x3d800000, v212
	s_and_saveexec_b64 s[0:1], s[6:7]
	s_waitcnt lgkmcnt(3)
	ds_write_b32 v167, v220
	s_or_b64 exec, exec, s[0:1]
	s_waitcnt lgkmcnt(1)
	v_cndmask_b32_e64 v226, v226, 0, s[6:7]
	v_cndmask_b32_e64 v227, 0, v227, s[12:13]
	v_add_f32_e32 v226, v226, v227
	v_cndmask_b32_e64 v227, 0, v228, s[8:9]
	v_add_f32_e32 v211, v226, v227
	v_add_f32_e32 v226, v209, v211
	ds_bpermute_b32 v221, v66, v226
	ds_bpermute_b32 v229, v2, v213
	ds_bpermute_b32 v230, v67, v213
	ds_bpermute_b32 v231, v68, v213
	v_add_f32_e32 v54, v141, v55
	v_min_f32_e32 v55, 0, v54
	v_mul_f32_e64 v54, |v54|, s73
	v_exp_f32_e32 v54, v54
	s_nop 0
	v_add_f32_e32 v54, 1.0, v54
	v_log_f32_e32 v54, v54
	s_nop 0
	v_mul_f32_e32 v58, 0x3f317217, v54
	v_fma_f32 v58, v54, s67, -v58
	v_fmac_f32_e32 v58, 0x3377d1cf, v54
	v_fmac_f32_e32 v58, 0x3f317217, v54
	v_mov_b32_e32 v54, v58
	v_mov_b32_e32 v58, 0
	v_sub_f32_e32 v54, v54, v58
	v_sub_f32_e32 v54, v55, v54
	v_add_f32_e32 v55, v141, v56
	v_min_f32_e32 v56, 0, v55
	v_mul_f32_e64 v55, |v55|, s73
	v_exp_f32_e32 v55, v55
	v_fmamk_f32 v218, v54, 0x3d800000, v96
	v_add_f32_e32 v55, 1.0, v55
	v_log_f32_e32 v55, v55
	s_nop 0
	v_mul_f32_e32 v58, 0x3f317217, v55
	v_fma_f32 v58, v55, s67, -v58
	v_fmac_f32_e32 v58, 0x3377d1cf, v55
	v_fmac_f32_e32 v58, 0x3f317217, v55
	v_mov_b32_e32 v55, v58
	v_mov_b32_e32 v58, 0
	v_sub_f32_e32 v55, v55, v58
	v_sub_f32_e32 v55, v56, v55
	v_add_f32_e32 v56, v141, v57
	v_min_f32_e32 v57, 0, v56
	v_mul_f32_e64 v56, |v56|, s73
	v_exp_f32_e32 v56, v56
	v_fmamk_f32 v216, v55, 0x3d800000, v218
	v_add_f32_e32 v56, 1.0, v56
	v_log_f32_e32 v56, v56
	s_nop 0
	v_mul_f32_e32 v58, 0x3f317217, v56
	v_fma_f32 v58, v56, s67, -v58
	v_fmac_f32_e32 v58, 0x3377d1cf, v56
	v_fmac_f32_e32 v58, 0x3f317217, v56
	v_mov_b32_e32 v56, v58
	v_mov_b32_e32 v58, 0
	v_sub_f32_e32 v56, v56, v58
	v_sub_f32_e32 v56, v57, v56
	v_fmamk_f32 v217, v56, 0x3d800000, v216
	s_and_saveexec_b64 s[0:1], s[6:7]
	s_waitcnt lgkmcnt(3)
	ds_write_b32 v167, v221 offset:64
	s_or_b64 exec, exec, s[0:1]
	s_waitcnt lgkmcnt(1)
	v_cndmask_b32_e64 v229, v229, 0, s[6:7]
	v_cndmask_b32_e64 v230, 0, v230, s[12:13]
	v_add_f32_e32 v229, v229, v230
	v_cndmask_b32_e64 v230, 0, v231, s[8:9]
	v_add_f32_e32 v215, v229, v230
	v_add_f32_e32 v229, v213, v215
	ds_bpermute_b32 v222, v66, v229
	ds_bpermute_b32 v2, v2, v217
	ds_bpermute_b32 v54, v67, v217
	ds_bpermute_b32 v55, v68, v217
	s_waitcnt lgkmcnt(2)
	v_cndmask_b32_e64 v2, v2, 0, s[6:7]
	s_waitcnt lgkmcnt(1)
	v_cndmask_b32_e64 v54, 0, v54, s[12:13]
	v_add_f32_e32 v2, v2, v54
	s_waitcnt lgkmcnt(0)
	v_cndmask_b32_e64 v54, 0, v55, s[8:9]
	v_add_f32_e32 v219, v2, v54
	v_add_f32_e32 v2, v217, v219
	ds_bpermute_b32 v2, v66, v2
	s_and_saveexec_b64 s[0:1], s[6:7]
	ds_write_b32 v167, v222 offset:128
	s_or_b64 exec, exec, s[0:1]
	s_and_saveexec_b64 s[0:1], s[6:7]
	s_cbranch_execz .LBB0_302
	s_waitcnt lgkmcnt(0)
	ds_write_b32 v167, v2 offset:192
	s_branch .LBB0_302
